# phase-0 ctx-silu loop (6 serial load-wait iterations) unrolled: 6 loads in flight, counted vmcnt waits; on top of the p_mods wide-batch version
# speedup vs baseline: 1.0015x; 1.0015x over previous
; #define LAS __attribute__((address_space(3)))
; DI float silu_f(float x) { return x * __builtin_amdgcn_rcpf(1.f + __builtin_amdgcn_exp2f(x * -1.4426950408889634f)); }
; DI void p_mods(const float* c, const float* cctx, const float* ada_w, const float* ada_b, float* mods, LAS float* sl, int bx, int G) {
;     ...
;     LAS float* part = sl + 3 * DM;
;     for (int i = tid; i < 3 * DM; i += NTHR) { const float v = (i < 2 * DM) ? c[i] : cctx[i - 2 * DM]; sl[i] = silu_f(v); }
;     __syncthreads();
.LBB0_10:
	global_load_dword v56, v[6:7], off
	global_load_dword v57, v[6:7], off offset:2048
	v_lshl_add_u64 v[10:11], v[6:7], 0, s[12:13]
	v_lshl_add_u64 v[10:11], v[10:11], 0, s[12:13]
	global_load_dword v58, v[10:11], off
	global_load_dword v59, v[10:11], off offset:2048
	v_lshl_add_u64 v[10:11], v[8:9], 2, s[46:47]
	global_load_dword v60, v[10:11], off
	global_load_dword v61, v[10:11], off offset:2048
	s_waitcnt vmcnt(5)
	v_mul_f32_e32 v10, 0xbfb8aa3b, v56
	v_exp_f32_e32 v10, v10
	s_nop 0
	v_add_f32_e32 v11, 1.0, v10
	v_rcp_f32_e32 v10, v11
	s_nop 0
	v_mul_f32_e32 v3, v56, v10
	ds_write_b32 v1, v3
	s_waitcnt vmcnt(4)
	v_mul_f32_e32 v10, 0xbfb8aa3b, v57
	v_exp_f32_e32 v10, v10
	s_nop 0
	v_add_f32_e32 v11, 1.0, v10
	v_rcp_f32_e32 v10, v11
	s_nop 0
	v_mul_f32_e32 v3, v57, v10
	ds_write_b32 v1, v3 offset:2048
	s_waitcnt vmcnt(3)
	v_mul_f32_e32 v10, 0xbfb8aa3b, v58
	v_exp_f32_e32 v10, v10
	s_nop 0
	v_add_f32_e32 v11, 1.0, v10
	v_rcp_f32_e32 v10, v11
	s_nop 0
	v_mul_f32_e32 v3, v58, v10
	ds_write_b32 v1, v3 offset:4096
	s_waitcnt vmcnt(2)
	v_mul_f32_e32 v10, 0xbfb8aa3b, v59
	v_exp_f32_e32 v10, v10
	s_nop 0
	v_add_f32_e32 v11, 1.0, v10
	v_rcp_f32_e32 v10, v11
	s_nop 0
	v_mul_f32_e32 v3, v59, v10
	ds_write_b32 v1, v3 offset:6144
	s_waitcnt vmcnt(1)
	v_mul_f32_e32 v10, 0xbfb8aa3b, v60
	v_exp_f32_e32 v10, v10
	s_nop 0
	v_add_f32_e32 v11, 1.0, v10
	v_rcp_f32_e32 v10, v11
	s_nop 0
	v_mul_f32_e32 v3, v60, v10
	ds_write_b32 v1, v3 offset:8192
	s_waitcnt vmcnt(0)
	v_mul_f32_e32 v10, 0xbfb8aa3b, v61
	v_exp_f32_e32 v10, v10
	s_nop 0
	v_add_f32_e32 v11, 1.0, v10
	v_rcp_f32_e32 v10, v11
	s_nop 0
	v_mul_f32_e32 v3, v61, v10
	ds_write_b32 v1, v3 offset:10240
